# code placement: the three GEMM K-loop heads aligned to 64 bytes
# baseline (speedup 1.0000x reference)
; #define PG8_BAR __builtin_amdgcn_s_barrier()
; DI void gemm_phase(LAS unsigned char* lds, const Gemm g, const StaticOrder& S, const EpiBf16& E) {
;     ...
;         const bool has_next = S.next(ui + 1, nxt);
;         const char* nA = has_next ? (const char*)g.A + (size_t)nxt.pm * tstep : cA; const char* nB = has_next ? (const char*)g.Bt + (size_t)nxt.pn * tstep : cB;
;         for (int t = 0; t < nt; t += 2) {
;             const bool last = (t == nt - 2);
;             const char* a1 = cA + (size_t)(t + 1) * kstep;
;             const char* a2 = last ? nA : cA + (size_t)(t + 2) * kstep; const char* b2 = last ? nB : cB + (size_t)(t + 2) * kstep;
;             const char* a3 = a2 + kstep; const char* b3 = b2 + kstep;
;             PG8_LDB(B0, 0, 0); PG8_SCHED; PG8_LDA(At, 0, 0); PG8_STAGE(PG8_SA(1, 1), a1 + hstep, voffA);
;             PG8_WAIT_L(8); PG8_BAR; PG8_WAIT_L(0); PG8_MMA(0, 0, At, B0); PG8_BAR; PG8_SCHED;
;             PG8_LDB(B1, 0, 1); PG8_STAGE(PG8_SB(0, 0), b2, voffB);
;             PG8_BAR; PG8_WAIT_L(0); PG8_MMA(0, 1, At, B1); PG8_BAR;
;             PG8_LDA(At, 0, 1); PG8_STAGE(PG8_SA(0, 0), a2, voffA);
;             PG8_BAR; PG8_WAIT_L(0); PG8_MMA(1, 0, At, B0); PG8_BAR; PG8_SCHED;
;             PG8_STAGE(PG8_SB(0, 1), b2 + hstep, voffB);
;             PG8_WAIT_V(6); PG8_BAR; PG8_MMA(1, 1, At, B1); PG8_BAR;
;             PG8_LDB(B0, 1, 0); PG8_SCHED; PG8_LDA(At, 1, 0); PG8_STAGE(PG8_SA(0, 1), a2 + hstep, voffA);
;             PG8_WAIT_L(8); PG8_BAR; PG8_WAIT_L(0); PG8_MMA(0, 0, At, B0); PG8_BAR; PG8_SCHED;
;             PG8_LDB(B1, 1, 1); PG8_STAGE(PG8_SB(1, 0), b3, voffB);
;             PG8_BAR; PG8_WAIT_L(0); PG8_MMA(0, 1, At, B1); PG8_BAR;
;             PG8_LDA(At, 1, 1); PG8_STAGE(PG8_SA(1, 0), a3, voffA);
;             PG8_BAR; PG8_WAIT_L(0); PG8_MMA(1, 0, At, B0); PG8_BAR; PG8_SCHED;
;             PG8_STAGE(PG8_SB(1, 1), b3 + hstep, voffB);
;             PG8_WAIT_V(6); PG8_BAR; PG8_MMA(1, 1, At, B1); PG8_BAR;
;         }
;         E(acc, cur, wr, wc, fr, fq);
;         if (!has_next) break;
; #pragma unroll
;         for (int a = 0; a < 2; ++a)
; #pragma unroll
;             for (int b = 0; b < 2; ++b)
; #pragma unroll
;                 for (int m = 0; m < 4; ++m)
; #pragma unroll
;                     for (int n = 0; n < 2; ++n) acc[a][b][m][n] = (f32x4){0.f, 0.f, 0.f, 0.f};
;         cur = nxt; cA = nA; cB = nB; ++ui;
.LBB0_180:
	v_mov_b64_e32 v[0:1], 0x3f0
	s_ashr_i32 s45, s44, 31
	v_cmp_lt_i64_e32 vcc, s[46:47], v[0:1]
	s_lshl_b64 s[46:47], s[44:45], 20
	s_add_u32 s46, s21, s46
	s_addc_u32 s47, s22, s47
	s_and_b64 s[48:49], vcc, exec
	s_cselect_b32 s45, s47, s51
	s_cselect_b32 s69, s46, s50
	s_ashr_i32 s43, s42, 31
	s_lshl_b64 s[48:49], s[42:43], 20
	s_add_u32 s48, s24, s48
	s_addc_u32 s49, s26, s49
	s_and_b64 s[54:55], vcc, exec
	s_cselect_b32 s43, s49, s53
	s_cselect_b32 s70, s48, s52
	s_add_u32 s50, s50, 0x80080
	s_addc_u32 s51, s51, 0
	s_add_u32 s71, s52, 0x100
	v_mov_b32_e32 v0, 0
	s_addc_u32 s72, s53, 0
	s_mov_b32 s73, -2
	v_mov_b32_e32 v1, v0
	v_mov_b32_e32 v2, v0
	v_mov_b32_e32 v3, v0
	v_mov_b32_e32 v4, v0
	v_mov_b32_e32 v5, v0
	v_mov_b32_e32 v6, v0
	v_mov_b32_e32 v7, v0
	v_mov_b32_e32 v8, v0
	v_mov_b32_e32 v9, v0
	v_mov_b32_e32 v10, v0
	v_mov_b32_e32 v11, v0
	v_mov_b32_e32 v12, v0
	v_mov_b32_e32 v13, v0
	v_mov_b32_e32 v14, v0
	v_mov_b32_e32 v15, v0
	v_mov_b32_e32 v24, v0
	v_mov_b32_e32 v25, v0
	v_mov_b32_e32 v26, v0
	v_mov_b32_e32 v27, v0
	v_mov_b32_e32 v28, v0
	v_mov_b32_e32 v29, v0
	v_mov_b32_e32 v30, v0
	v_mov_b32_e32 v31, v0
	v_mov_b32_e32 v40, v0
	v_mov_b32_e32 v41, v0
	v_mov_b32_e32 v42, v0
	v_mov_b32_e32 v43, v0
	v_mov_b32_e32 v44, v0
	v_mov_b32_e32 v45, v0
	v_mov_b32_e32 v46, v0
	v_mov_b32_e32 v47, v0
	v_mov_b32_e32 v16, v0
	v_mov_b32_e32 v17, v0
	v_mov_b32_e32 v18, v0
	v_mov_b32_e32 v19, v0
	v_mov_b32_e32 v20, v0
	v_mov_b32_e32 v21, v0
	v_mov_b32_e32 v22, v0
	v_mov_b32_e32 v23, v0
	v_mov_b32_e32 v32, v0
	v_mov_b32_e32 v33, v0
	v_mov_b32_e32 v34, v0
	v_mov_b32_e32 v35, v0
	v_mov_b32_e32 v36, v0
	v_mov_b32_e32 v37, v0
	v_mov_b32_e32 v38, v0
	v_mov_b32_e32 v39, v0
	v_mov_b32_e32 v48, v0
	v_mov_b32_e32 v49, v0
	v_mov_b32_e32 v50, v0
	v_mov_b32_e32 v51, v0
	v_mov_b32_e32 v52, v0
	v_mov_b32_e32 v53, v0
	v_mov_b32_e32 v54, v0
	v_mov_b32_e32 v55, v0
	v_mov_b32_e32 v56, v0
	v_mov_b32_e32 v57, v0
	v_mov_b32_e32 v58, v0
	v_mov_b32_e32 v59, v0
	v_mov_b32_e32 v60, v0
	v_mov_b32_e32 v61, v0
	v_mov_b32_e32 v62, v0
	v_mov_b32_e32 v63, v0
	v_mov_b32_e32 v64, v0
	v_mov_b32_e32 v65, v0
	v_mov_b32_e32 v66, v0
	v_mov_b32_e32 v67, v0
	v_mov_b32_e32 v68, v0
	v_mov_b32_e32 v69, v0
	v_mov_b32_e32 v70, v0
	v_mov_b32_e32 v71, v0
	v_mov_b32_e32 v72, v0
	v_mov_b32_e32 v73, v0
	v_mov_b32_e32 v74, v0
	v_mov_b32_e32 v75, v0
	v_mov_b32_e32 v76, v0
	v_mov_b32_e32 v77, v0
	v_mov_b32_e32 v78, v0
	v_mov_b32_e32 v79, v0
	v_mov_b32_e32 v88, v0
	v_mov_b32_e32 v89, v0
	v_mov_b32_e32 v90, v0
	v_mov_b32_e32 v91, v0
	v_mov_b32_e32 v92, v0
	v_mov_b32_e32 v93, v0
	v_mov_b32_e32 v94, v0
	v_mov_b32_e32 v95, v0
	v_mov_b32_e32 v104, v0
	v_mov_b32_e32 v105, v0
	v_mov_b32_e32 v106, v0
	v_mov_b32_e32 v107, v0
	v_mov_b32_e32 v108, v0
	v_mov_b32_e32 v109, v0
	v_mov_b32_e32 v110, v0
	v_mov_b32_e32 v111, v0
	v_mov_b32_e32 v80, v0
	v_mov_b32_e32 v81, v0
	v_mov_b32_e32 v82, v0
	v_mov_b32_e32 v83, v0
	v_mov_b32_e32 v84, v0
	v_mov_b32_e32 v85, v0
	v_mov_b32_e32 v86, v0
	v_mov_b32_e32 v87, v0
	v_mov_b32_e32 v96, v0
	v_mov_b32_e32 v97, v0
	v_mov_b32_e32 v98, v0
	v_mov_b32_e32 v99, v0
	v_mov_b32_e32 v100, v0
	v_mov_b32_e32 v101, v0
	v_mov_b32_e32 v102, v0
	v_mov_b32_e32 v103, v0
	v_mov_b32_e32 v112, v0
	v_mov_b32_e32 v113, v0
	v_mov_b32_e32 v114, v0
	v_mov_b32_e32 v115, v0
	v_mov_b32_e32 v116, v0
	v_mov_b32_e32 v117, v0
	v_mov_b32_e32 v118, v0
	v_mov_b32_e32 v119, v0
	v_mov_b32_e32 v120, v0
	v_mov_b32_e32 v121, v0
	v_mov_b32_e32 v122, v0
	v_mov_b32_e32 v123, v0
	v_mov_b32_e32 v124, v0
	v_mov_b32_e32 v125, v0
	v_mov_b32_e32 v126, v0
	v_mov_b32_e32 v127, v0
	.p2alignl 6, 3212836864

; #define PG8_BAR __builtin_amdgcn_s_barrier()
; DI void gemm_phase(LAS unsigned char* lds, const Gemm g, const StaticOrder& S, const EpiBf16& E) {
;     ...
;         const bool has_next = S.next(ui + 1, nxt);
;         const char* nA = has_next ? (const char*)g.A + (size_t)nxt.pm * tstep : cA; const char* nB = has_next ? (const char*)g.Bt + (size_t)nxt.pn * tstep : cB;
;         for (int t = 0; t < nt; t += 2) {
;             const bool last = (t == nt - 2);
;             const char* a1 = cA + (size_t)(t + 1) * kstep;
;             const char* a2 = last ? nA : cA + (size_t)(t + 2) * kstep; const char* b2 = last ? nB : cB + (size_t)(t + 2) * kstep;
;             const char* a3 = a2 + kstep; const char* b3 = b2 + kstep;
;             PG8_LDB(B0, 0, 0); PG8_SCHED; PG8_LDA(At, 0, 0); PG8_STAGE(PG8_SA(1, 1), a1 + hstep, voffA);
;             PG8_WAIT_L(8); PG8_BAR; PG8_WAIT_L(0); PG8_MMA(0, 0, At, B0); PG8_BAR; PG8_SCHED;
;             PG8_LDB(B1, 0, 1); PG8_STAGE(PG8_SB(0, 0), b2, voffB);
;             PG8_BAR; PG8_WAIT_L(0); PG8_MMA(0, 1, At, B1); PG8_BAR;
;             PG8_LDA(At, 0, 1); PG8_STAGE(PG8_SA(0, 0), a2, voffA);
;             PG8_BAR; PG8_WAIT_L(0); PG8_MMA(1, 0, At, B0); PG8_BAR; PG8_SCHED;
;             PG8_STAGE(PG8_SB(0, 1), b2 + hstep, voffB);
;             PG8_WAIT_V(6); PG8_BAR; PG8_MMA(1, 1, At, B1); PG8_BAR;
;             PG8_LDB(B0, 1, 0); PG8_SCHED; PG8_LDA(At, 1, 0); PG8_STAGE(PG8_SA(0, 1), a2 + hstep, voffA);
;             PG8_WAIT_L(8); PG8_BAR; PG8_WAIT_L(0); PG8_MMA(0, 0, At, B0); PG8_BAR; PG8_SCHED;
;             PG8_LDB(B1, 1, 1); PG8_STAGE(PG8_SB(1, 0), b3, voffB);
;             PG8_BAR; PG8_WAIT_L(0); PG8_MMA(0, 1, At, B1); PG8_BAR;
;             PG8_LDA(At, 1, 1); PG8_STAGE(PG8_SA(1, 0), a3, voffA);
;             PG8_BAR; PG8_WAIT_L(0); PG8_MMA(1, 0, At, B0); PG8_BAR; PG8_SCHED;
;             PG8_STAGE(PG8_SB(1, 1), b3 + hstep, voffB);
;             PG8_WAIT_V(6); PG8_BAR; PG8_MMA(1, 1, At, B1); PG8_BAR;
;         }
;         E(acc, cur, wr, wc, fr, fq);
;         if (!has_next) break;
; #pragma unroll
;         for (int a = 0; a < 2; ++a)
; #pragma unroll
;             for (int b = 0; b < 2; ++b)
; #pragma unroll
;                 for (int m = 0; m < 4; ++m)
; #pragma unroll
;                     for (int n = 0; n < 2; ++n) acc[a][b][m][n] = (f32x4){0.f, 0.f, 0.f, 0.f};
;         cur = nxt; cA = nA; cB = nB; ++ui;
.LBB0_744:
	s_ashr_i32 s43, s42, 31
	s_lshl_b64 s[4:5], s[42:43], 20
	v_cmp_lt_i64_e32 vcc, s[44:45], v[140:141]
	s_add_u32 s44, s22, s4
	s_addc_u32 s45, s24, s5
	s_and_b64 s[4:5], vcc, exec
	s_cselect_b32 s43, s45, s49
	s_cselect_b32 s70, s44, s48
	s_ashr_i32 s41, s40, 31
	s_lshl_b64 s[4:5], s[40:41], 20
	s_add_u32 s46, s26, s4
	s_addc_u32 s47, s27, s5
	s_and_b64 s[4:5], vcc, exec
	s_cselect_b32 s41, s47, s51
	s_cselect_b32 s71, s46, s50
	s_add_u32 s48, s48, 0x80080
	s_addc_u32 s49, s49, 0
	s_add_u32 s72, s50, 0x100
	v_mov_b32_e32 v0, 0
	s_addc_u32 s73, s51, 0
	s_mov_b32 s74, -2
	v_mov_b32_e32 v1, v0
	v_mov_b32_e32 v2, v0
	v_mov_b32_e32 v3, v0
	v_mov_b32_e32 v4, v0
	v_mov_b32_e32 v5, v0
	v_mov_b32_e32 v6, v0
	v_mov_b32_e32 v7, v0
	v_mov_b32_e32 v8, v0
	v_mov_b32_e32 v9, v0
	v_mov_b32_e32 v10, v0
	v_mov_b32_e32 v11, v0
	v_mov_b32_e32 v12, v0
	v_mov_b32_e32 v13, v0
	v_mov_b32_e32 v14, v0
	v_mov_b32_e32 v15, v0
	v_mov_b32_e32 v24, v0
	v_mov_b32_e32 v25, v0
	v_mov_b32_e32 v26, v0
	v_mov_b32_e32 v27, v0
	v_mov_b32_e32 v28, v0
	v_mov_b32_e32 v29, v0
	v_mov_b32_e32 v30, v0
	v_mov_b32_e32 v31, v0
	v_mov_b32_e32 v40, v0
	v_mov_b32_e32 v41, v0
	v_mov_b32_e32 v42, v0
	v_mov_b32_e32 v43, v0
	v_mov_b32_e32 v44, v0
	v_mov_b32_e32 v45, v0
	v_mov_b32_e32 v46, v0
	v_mov_b32_e32 v47, v0
	v_mov_b32_e32 v16, v0
	v_mov_b32_e32 v17, v0
	v_mov_b32_e32 v18, v0
	v_mov_b32_e32 v19, v0
	v_mov_b32_e32 v20, v0
	v_mov_b32_e32 v21, v0
	v_mov_b32_e32 v22, v0
	v_mov_b32_e32 v23, v0
	v_mov_b32_e32 v32, v0
	v_mov_b32_e32 v33, v0
	v_mov_b32_e32 v34, v0
	v_mov_b32_e32 v35, v0
	v_mov_b32_e32 v36, v0
	v_mov_b32_e32 v37, v0
	v_mov_b32_e32 v38, v0
	v_mov_b32_e32 v39, v0
	v_mov_b32_e32 v48, v0
	v_mov_b32_e32 v49, v0
	v_mov_b32_e32 v50, v0
	v_mov_b32_e32 v51, v0
	v_mov_b32_e32 v52, v0
	v_mov_b32_e32 v53, v0
	v_mov_b32_e32 v54, v0
	v_mov_b32_e32 v55, v0
	v_mov_b32_e32 v56, v0
	v_mov_b32_e32 v57, v0
	v_mov_b32_e32 v58, v0
	v_mov_b32_e32 v59, v0
	v_mov_b32_e32 v60, v0
	v_mov_b32_e32 v61, v0
	v_mov_b32_e32 v62, v0
	v_mov_b32_e32 v63, v0
	v_mov_b32_e32 v64, v0
	v_mov_b32_e32 v65, v0
	v_mov_b32_e32 v66, v0
	v_mov_b32_e32 v67, v0
	v_mov_b32_e32 v68, v0
	v_mov_b32_e32 v69, v0
	v_mov_b32_e32 v70, v0
	v_mov_b32_e32 v71, v0
	v_mov_b32_e32 v72, v0
	v_mov_b32_e32 v73, v0
	v_mov_b32_e32 v74, v0
	v_mov_b32_e32 v75, v0
	v_mov_b32_e32 v76, v0
	v_mov_b32_e32 v77, v0
	v_mov_b32_e32 v78, v0
	v_mov_b32_e32 v79, v0
	v_mov_b32_e32 v88, v0
	v_mov_b32_e32 v89, v0
	v_mov_b32_e32 v90, v0
	v_mov_b32_e32 v91, v0
	v_mov_b32_e32 v92, v0
	v_mov_b32_e32 v93, v0
	v_mov_b32_e32 v94, v0
	v_mov_b32_e32 v95, v0
	v_mov_b32_e32 v104, v0
	v_mov_b32_e32 v105, v0
	v_mov_b32_e32 v106, v0
	v_mov_b32_e32 v107, v0
	v_mov_b32_e32 v108, v0
	v_mov_b32_e32 v109, v0
	v_mov_b32_e32 v110, v0
	v_mov_b32_e32 v111, v0
	v_mov_b32_e32 v80, v0
	v_mov_b32_e32 v81, v0
	v_mov_b32_e32 v82, v0
	v_mov_b32_e32 v83, v0
	v_mov_b32_e32 v84, v0
	v_mov_b32_e32 v85, v0
	v_mov_b32_e32 v86, v0
	v_mov_b32_e32 v87, v0
	v_mov_b32_e32 v96, v0
	v_mov_b32_e32 v97, v0
	v_mov_b32_e32 v98, v0
	v_mov_b32_e32 v99, v0
	v_mov_b32_e32 v100, v0
	v_mov_b32_e32 v101, v0
	v_mov_b32_e32 v102, v0
	v_mov_b32_e32 v103, v0
	v_mov_b32_e32 v112, v0
	v_mov_b32_e32 v113, v0
	v_mov_b32_e32 v114, v0
	v_mov_b32_e32 v115, v0
	v_mov_b32_e32 v116, v0
	v_mov_b32_e32 v117, v0
	v_mov_b32_e32 v118, v0
	v_mov_b32_e32 v119, v0
	v_mov_b32_e32 v120, v0
	v_mov_b32_e32 v121, v0
	v_mov_b32_e32 v122, v0
	v_mov_b32_e32 v123, v0
	v_mov_b32_e32 v124, v0
	v_mov_b32_e32 v125, v0
	v_mov_b32_e32 v126, v0
	v_mov_b32_e32 v127, v0
	.p2alignl 6, 3212836864

; #define PG8_BAR __builtin_amdgcn_s_barrier()
; DI void gemm_phase(LAS unsigned char* lds, const Gemm g, const StaticOrder& S, const EpiBf16& E) {
;     ...
;         const bool has_next = S.next(ui + 1, nxt);
;         const char* nA = has_next ? (const char*)g.A + (size_t)nxt.pm * tstep : cA; const char* nB = has_next ? (const char*)g.Bt + (size_t)nxt.pn * tstep : cB;
;         for (int t = 0; t < nt; t += 2) {
;             const bool last = (t == nt - 2);
;             const char* a1 = cA + (size_t)(t + 1) * kstep;
;             const char* a2 = last ? nA : cA + (size_t)(t + 2) * kstep; const char* b2 = last ? nB : cB + (size_t)(t + 2) * kstep;
;             const char* a3 = a2 + kstep; const char* b3 = b2 + kstep;
;             PG8_LDB(B0, 0, 0); PG8_SCHED; PG8_LDA(At, 0, 0); PG8_STAGE(PG8_SA(1, 1), a1 + hstep, voffA);
;             PG8_WAIT_L(8); PG8_BAR; PG8_WAIT_L(0); PG8_MMA(0, 0, At, B0); PG8_BAR; PG8_SCHED;
;             PG8_LDB(B1, 0, 1); PG8_STAGE(PG8_SB(0, 0), b2, voffB);
;             PG8_BAR; PG8_WAIT_L(0); PG8_MMA(0, 1, At, B1); PG8_BAR;
;             PG8_LDA(At, 0, 1); PG8_STAGE(PG8_SA(0, 0), a2, voffA);
;             PG8_BAR; PG8_WAIT_L(0); PG8_MMA(1, 0, At, B0); PG8_BAR; PG8_SCHED;
;             PG8_STAGE(PG8_SB(0, 1), b2 + hstep, voffB);
;             PG8_WAIT_V(6); PG8_BAR; PG8_MMA(1, 1, At, B1); PG8_BAR;
;             PG8_LDB(B0, 1, 0); PG8_SCHED; PG8_LDA(At, 1, 0); PG8_STAGE(PG8_SA(0, 1), a2 + hstep, voffA);
;             PG8_WAIT_L(8); PG8_BAR; PG8_WAIT_L(0); PG8_MMA(0, 0, At, B0); PG8_BAR; PG8_SCHED;
;             PG8_LDB(B1, 1, 1); PG8_STAGE(PG8_SB(1, 0), b3, voffB);
;             PG8_BAR; PG8_WAIT_L(0); PG8_MMA(0, 1, At, B1); PG8_BAR;
;             PG8_LDA(At, 1, 1); PG8_STAGE(PG8_SA(1, 0), a3, voffA);
;             PG8_BAR; PG8_WAIT_L(0); PG8_MMA(1, 0, At, B0); PG8_BAR; PG8_SCHED;
;             PG8_STAGE(PG8_SB(1, 1), b3 + hstep, voffB);
;             PG8_WAIT_V(6); PG8_BAR; PG8_MMA(1, 1, At, B1); PG8_BAR;
;         }
;         E(acc, cur, wr, wc, fr, fq);
;         if (!has_next) break;
; #pragma unroll
;         for (int a = 0; a < 2; ++a)
; #pragma unroll
;             for (int b = 0; b < 2; ++b)
; #pragma unroll
;                 for (int m = 0; m < 4; ++m)
; #pragma unroll
;                     for (int n = 0; n < 2; ++n) acc[a][b][m][n] = (f32x4){0.f, 0.f, 0.f, 0.f};
;         cur = nxt; cA = nA; cB = nB; ++ui;
.LBB0_836:
	s_ashr_i32 s41, s40, 31
	s_lshl_b64 s[4:5], s[40:41], 20
	v_cmp_lt_i64_e64 s[52:53], s[44:45], 32
	s_add_u32 s44, s24, s4
	s_addc_u32 s45, s26, s5
	s_and_b64 s[4:5], s[52:53], exec
	s_cselect_b32 s22, s45, s49
	s_cselect_b32 s41, s44, s48
	s_ashr_i32 s43, s42, 31
	s_lshl_b64 s[4:5], s[42:43], 20
	s_add_u32 s46, s27, s4
	s_addc_u32 s47, s30, s5
	s_and_b64 s[4:5], s[52:53], exec
	s_cselect_b32 s43, s47, s51
	s_cselect_b32 s71, s46, s50
	s_add_u32 s48, s48, 0x80080
	s_addc_u32 s49, s49, 0
	s_add_u32 s72, s50, 0x100
	v_mov_b32_e32 v0, 0
	s_addc_u32 s73, s51, 0
	s_mov_b32 s74, -2
	v_mov_b32_e32 v1, v0
	v_mov_b32_e32 v2, v0
	v_mov_b32_e32 v3, v0
	v_mov_b32_e32 v4, v0
	v_mov_b32_e32 v5, v0
	v_mov_b32_e32 v6, v0
	v_mov_b32_e32 v7, v0
	v_mov_b32_e32 v8, v0
	v_mov_b32_e32 v9, v0
	v_mov_b32_e32 v10, v0
	v_mov_b32_e32 v11, v0
	v_mov_b32_e32 v12, v0
	v_mov_b32_e32 v13, v0
	v_mov_b32_e32 v14, v0
	v_mov_b32_e32 v15, v0
	v_mov_b32_e32 v24, v0
	v_mov_b32_e32 v25, v0
	v_mov_b32_e32 v26, v0
	v_mov_b32_e32 v27, v0
	v_mov_b32_e32 v28, v0
	v_mov_b32_e32 v29, v0
	v_mov_b32_e32 v30, v0
	v_mov_b32_e32 v31, v0
	v_mov_b32_e32 v40, v0
	v_mov_b32_e32 v41, v0
	v_mov_b32_e32 v42, v0
	v_mov_b32_e32 v43, v0
	v_mov_b32_e32 v44, v0
	v_mov_b32_e32 v45, v0
	v_mov_b32_e32 v46, v0
	v_mov_b32_e32 v47, v0
	v_mov_b32_e32 v16, v0
	v_mov_b32_e32 v17, v0
	v_mov_b32_e32 v18, v0
	v_mov_b32_e32 v19, v0
	v_mov_b32_e32 v20, v0
	v_mov_b32_e32 v21, v0
	v_mov_b32_e32 v22, v0
	v_mov_b32_e32 v23, v0
	v_mov_b32_e32 v32, v0
	v_mov_b32_e32 v33, v0
	v_mov_b32_e32 v34, v0
	v_mov_b32_e32 v35, v0
	v_mov_b32_e32 v36, v0
	v_mov_b32_e32 v37, v0
	v_mov_b32_e32 v38, v0
	v_mov_b32_e32 v39, v0
	v_mov_b32_e32 v48, v0
	v_mov_b32_e32 v49, v0
	v_mov_b32_e32 v50, v0
	v_mov_b32_e32 v51, v0
	v_mov_b32_e32 v52, v0
	v_mov_b32_e32 v53, v0
	v_mov_b32_e32 v54, v0
	v_mov_b32_e32 v55, v0
	v_mov_b32_e32 v56, v0
	v_mov_b32_e32 v57, v0
	v_mov_b32_e32 v58, v0
	v_mov_b32_e32 v59, v0
	v_mov_b32_e32 v60, v0
	v_mov_b32_e32 v61, v0
	v_mov_b32_e32 v62, v0
	v_mov_b32_e32 v63, v0
	v_mov_b32_e32 v64, v0
	v_mov_b32_e32 v65, v0
	v_mov_b32_e32 v66, v0
	v_mov_b32_e32 v67, v0
	v_mov_b32_e32 v68, v0
	v_mov_b32_e32 v69, v0
	v_mov_b32_e32 v70, v0
	v_mov_b32_e32 v71, v0
	v_mov_b32_e32 v72, v0
	v_mov_b32_e32 v73, v0
	v_mov_b32_e32 v74, v0
	v_mov_b32_e32 v75, v0
	v_mov_b32_e32 v76, v0
	v_mov_b32_e32 v77, v0
	v_mov_b32_e32 v78, v0
	v_mov_b32_e32 v79, v0
	v_mov_b32_e32 v88, v0
	v_mov_b32_e32 v89, v0
	v_mov_b32_e32 v90, v0
	v_mov_b32_e32 v91, v0
	v_mov_b32_e32 v92, v0
	v_mov_b32_e32 v93, v0
	v_mov_b32_e32 v94, v0
	v_mov_b32_e32 v95, v0
	v_mov_b32_e32 v104, v0
	v_mov_b32_e32 v105, v0
	v_mov_b32_e32 v106, v0
	v_mov_b32_e32 v107, v0
	v_mov_b32_e32 v108, v0
	v_mov_b32_e32 v109, v0
	v_mov_b32_e32 v110, v0
	v_mov_b32_e32 v111, v0
	v_mov_b32_e32 v80, v0
	v_mov_b32_e32 v81, v0
	v_mov_b32_e32 v82, v0
	v_mov_b32_e32 v83, v0
	v_mov_b32_e32 v84, v0
	v_mov_b32_e32 v85, v0
	v_mov_b32_e32 v86, v0
	v_mov_b32_e32 v87, v0
	v_mov_b32_e32 v96, v0
	v_mov_b32_e32 v97, v0
	v_mov_b32_e32 v98, v0
	v_mov_b32_e32 v99, v0
	v_mov_b32_e32 v100, v0
	v_mov_b32_e32 v101, v0
	v_mov_b32_e32 v102, v0
	v_mov_b32_e32 v103, v0
	v_mov_b32_e32 v112, v0
	v_mov_b32_e32 v113, v0
	v_mov_b32_e32 v114, v0
	v_mov_b32_e32 v115, v0
	v_mov_b32_e32 v116, v0
	v_mov_b32_e32 v117, v0
	v_mov_b32_e32 v118, v0
	v_mov_b32_e32 v119, v0
	v_mov_b32_e32 v120, v0
	v_mov_b32_e32 v121, v0
	v_mov_b32_e32 v122, v0
	v_mov_b32_e32 v123, v0
	v_mov_b32_e32 v124, v0
	v_mov_b32_e32 v125, v0
	v_mov_b32_e32 v126, v0
	v_mov_b32_e32 v127, v0
	.p2alignl 6, 3212836864
